# grid barrier: non-leader blocks keep two staggered TOPGEN polls in flight (pipelined polling, half the release-detection latency)
# baseline (speedup 1.0000x reference)
; __device__ __forceinline__ unsigned xb_ld(unsigned* p)              { return __hip_atomic_load(p, __ATOMIC_RELAXED, __HIP_MEMORY_SCOPE_AGENT); }
; __device__ __forceinline__ unsigned xb_add(unsigned* p, unsigned v) { return __hip_atomic_fetch_add(p, v, __ATOMIC_RELAXED, __HIP_MEMORY_SCOPE_AGENT); }
; #define XB_SPIN(cond, bar) do { unsigned _sp = 0; while (cond) { __builtin_amdgcn_s_sleep(1); \
;     if ((++_sp & 255u) == 0u) { if (xb_ld(&(bar)[XB_TMO])) break; if (_sp > XB_SPIN_CAP) { atomicAdd(&(bar)[XB_TMO], 1u); break; } } } } while (0)
; __device__ __forceinline__ void xcd_barrier(const XcdBarrier& b) {
;     ...
;             const unsigned tg = og / nx;
;             if (og + 1u == (tg + 1u) * nx) xb_add(&bar[XB_TOPGEN], 1u);
;             else XB_SPIN(xb_ld(&bar[XB_TOPGEN]) == tg, bar);
.LBB0_533:
	s_or_b64 exec, exec, s[12:13]
	v_cvt_f32_u32_e32 v5, v3
	s_waitcnt vmcnt(0)
	v_readfirstlane_b32 s2, v4
	v_sub_u32_e32 v4, 0, v3
	v_rcp_iflag_f32_e32 v5, v5
	v_add_u32_e32 v6, s2, v2
	v_mul_f32_e32 v5, 0x4f7ffffe, v5
	v_cvt_u32_f32_e32 v5, v5
	v_mul_lo_u32 v2, v4, v5
	v_mul_hi_u32 v2, v5, v2
	v_add_u32_e32 v2, v5, v2
	v_mul_hi_u32 v2, v6, v2
	v_mul_lo_u32 v4, v2, v3
	v_sub_u32_e32 v4, v6, v4
	v_add_u32_e32 v5, 1, v2
	v_cmp_ge_u32_e32 vcc, v4, v3
	s_nop 1
	v_cndmask_b32_e32 v2, v2, v5, vcc
	v_sub_u32_e32 v5, v4, v3
	v_cndmask_b32_e32 v4, v4, v5, vcc
	v_add_u32_e32 v5, 1, v2
	v_cmp_ge_u32_e32 vcc, v4, v3
	v_add_u32_e32 v4, 1, v6
	s_nop 0
	v_cndmask_b32_e32 v2, v2, v5, vcc
	v_mul_lo_u32 v5, v3, v2
	v_add_u32_e32 v3, v5, v3
	v_cmp_ne_u32_e32 vcc, v4, v3
	s_and_saveexec_b64 s[10:11], vcc
	s_xor_b64 s[10:11], exec, s[10:11]
	s_cbranch_execz .LBB0_547
	s_waitcnt lgkmcnt(0)
	s_add_u32 s16, s6, 0x32c03500
	s_addc_u32 s17, s7, 0
	s_add_i32 s2, s80, -1
	v_mov_b32_e32 v2, s2
	s_mov_b64 s[12:13], exec
	buffer_inv sc1
	global_load_dword v0, v1, s[16:17] sc1
	s_sleep 12
	global_load_dword v3, v1, s[16:17] sc1
	s_mov_b32 s2, 0
.Lgb_poll:
	s_waitcnt vmcnt(1)
	v_cmp_ne_u32_e32 vcc, v0, v2
	s_cbranch_vccnz .LBB0_546
	global_load_dword v0, v1, s[16:17] sc1
	s_waitcnt vmcnt(1)
	v_cmp_ne_u32_e32 vcc, v3, v2
	s_cbranch_vccnz .LBB0_546
	global_load_dword v3, v1, s[16:17] sc1
	s_add_i32 s2, s2, 1
	s_cmp_lt_u32 s2, 0x100000
	s_cbranch_scc1 .Lgb_poll
